# n3 interior softmax: dropped the redundant 0+p0 add that seeds each row-sum chain (2 VALU per tile)
# speedup vs baseline: 1.0004x; 1.0004x over previous
.LBB0_64:
	s_andn2_b64 vcc, exec, s[20:21]
	s_cbranch_vccnz .LBB0_66
	v_max3_f32 v0, v96, s60, v97
	v_max3_f32 v0, v0, v98, v99
	v_max3_f32 v0, v0, v92, v93
	v_max3_f32 v0, v0, v94, v95
	v_max3_f32 v0, v0, v88, v89
	v_max3_f32 v0, v0, v90, v91
	v_max3_f32 v0, v0, v84, v85
	v_max3_f32 v0, v0, v86, v87
	v_cndmask_b32_e64 v0, v146, v0, s[38:39]
	v_mov_b32_e32 v2, v0
	s_waitcnt lgkmcnt(0)
	s_nop 1
	v_permlane16_swap_b32_e32 v2, v0
	v_max_f32_e32 v2, v2, v2
	v_max_f32_e32 v0, v0, v2
	v_mov_b32_e32 v2, v0
	s_nop 1
	v_permlane32_swap_b32_e32 v2, v0
	v_max3_f32 v3, v217, v0, v2
	v_cndmask_b32_e64 v148, v147, v3, s[38:39]
	v_sub_f32_e32 v2, v96, v148
	v_sub_f32_e32 v96, v97, v148
	v_exp_f32_e32 v2, v2
	v_sub_f32_e32 v97, v98, v148
	v_exp_f32_e32 v218, v96
	v_sub_f32_e32 v98, v99, v148
	v_exp_f32_e32 v219, v97
	v_sub_f32_e32 v92, v92, v148
	v_exp_f32_e32 v220, v98
	v_sub_f32_e32 v93, v93, v148
	v_exp_f32_e32 v221, v92
	v_add_f32_e32 v92, v218, v2
	v_exp_f32_e32 v222, v93
	v_sub_f32_e32 v93, v94, v148
	v_add_f32_e32 v92, v219, v92
	v_exp_f32_e32 v223, v93
	v_sub_f32_e32 v93, v95, v148
	v_add_f32_e32 v92, v220, v92
	v_exp_f32_e32 v224, v93
	v_sub_f32_e32 v88, v88, v148
	v_add_f32_e32 v92, v221, v92
	v_exp_f32_e32 v225, v88
	v_sub_f32_e32 v88, v89, v148
	v_add_f32_e32 v92, v222, v92
	v_exp_f32_e32 v226, v88
	v_sub_f32_e32 v88, v90, v148
	v_add_f32_e32 v92, v223, v92
	v_exp_f32_e32 v227, v88
	v_sub_f32_e32 v88, v91, v148
	v_add_f32_e32 v92, v224, v92
	v_exp_f32_e32 v228, v88
	v_sub_f32_e32 v84, v84, v148
	v_add_f32_e32 v88, v225, v92
	v_exp_f32_e32 v229, v84
	v_sub_f32_e32 v84, v85, v148
	v_add_f32_e32 v88, v226, v88
	v_exp_f32_e32 v230, v84
	v_sub_f32_e32 v84, v86, v148
	v_add_f32_e32 v88, v227, v88
	v_exp_f32_e32 v231, v84
	v_sub_f32_e32 v84, v87, v148
	v_sub_f32_e32 v0, v217, v3
	v_add_f32_e32 v88, v228, v88
	v_exp_f32_e32 v232, v84
	v_exp_f32_e32 v0, v0
	v_add_f32_e32 v84, v229, v88
	v_add_f32_e32 v84, v230, v84
	v_add_f32_e32 v84, v231, v84
	v_add_f32_e32 v216, v232, v84

.LBB0_68:
	s_andn2_b64 vcc, exec, s[0:1]
	s_cbranch_vccnz .LBB0_70
	v_max3_f32 v2, v80, s60, v81
	v_max3_f32 v2, v2, v82, v83
	v_max3_f32 v2, v2, v72, v73
	v_max3_f32 v2, v2, v74, v75
	v_max3_f32 v2, v2, v68, v69
	v_max3_f32 v2, v2, v70, v71
	v_max3_f32 v2, v2, v76, v77
	v_max3_f32 v2, v2, v78, v79
	v_cndmask_b32_e64 v2, v146, v2, s[38:39]
	v_mov_b32_e32 v92, v2
	s_waitcnt lgkmcnt(0)
	s_nop 1
	v_permlane16_swap_b32_e32 v92, v2
	v_max_f32_e32 v92, v92, v92
	v_max_f32_e32 v2, v2, v92
	v_mov_b32_e32 v92, v2
	s_nop 1
	v_permlane32_swap_b32_e32 v92, v2
	v_max3_f32 v92, v215, v2, v92
	v_cndmask_b32_e64 v93, v147, v92, s[38:39]
	v_sub_f32_e32 v80, v80, v93
	v_sub_f32_e32 v81, v81, v93
	v_exp_f32_e32 v94, v80
	v_sub_f32_e32 v82, v82, v93
	v_exp_f32_e32 v95, v81
	v_sub_f32_e32 v83, v83, v93
	v_exp_f32_e32 v96, v82
	v_sub_f32_e32 v72, v72, v93
	v_exp_f32_e32 v97, v83
	v_sub_f32_e32 v73, v73, v93
	v_exp_f32_e32 v98, v72
	v_add_f32_e32 v72, v95, v94
	v_exp_f32_e32 v99, v73
	v_sub_f32_e32 v73, v74, v93
	v_add_f32_e32 v72, v96, v72
	v_exp_f32_e32 v217, v73
	v_sub_f32_e32 v73, v75, v93
	v_add_f32_e32 v72, v97, v72
	v_exp_f32_e32 v218, v73
	v_sub_f32_e32 v68, v68, v93
	v_add_f32_e32 v72, v98, v72
	v_exp_f32_e32 v219, v68
	v_sub_f32_e32 v68, v69, v93
	v_add_f32_e32 v72, v99, v72
	v_exp_f32_e32 v220, v68
	v_sub_f32_e32 v68, v70, v93
	v_add_f32_e32 v72, v217, v72
	v_exp_f32_e32 v221, v68
	v_sub_f32_e32 v68, v71, v93
	v_add_f32_e32 v72, v218, v72
	v_exp_f32_e32 v222, v68
	v_sub_f32_e32 v69, v76, v93
	v_add_f32_e32 v68, v219, v72
	v_exp_f32_e32 v223, v69
	v_sub_f32_e32 v69, v77, v93
	v_add_f32_e32 v68, v220, v68
	v_exp_f32_e32 v224, v69
	v_sub_f32_e32 v69, v78, v93
	v_add_f32_e32 v68, v221, v68
	v_exp_f32_e32 v225, v69
	v_sub_f32_e32 v69, v79, v93
	v_sub_f32_e32 v2, v215, v92
	v_add_f32_e32 v68, v222, v68
	v_exp_f32_e32 v226, v69
	v_exp_f32_e32 v2, v2
	v_add_f32_e32 v68, v223, v68
	v_add_f32_e32 v68, v224, v68
	v_add_f32_e32 v68, v225, v68
	v_add_f32_e32 v93, v226, v68
